# mid kv-up units: column tile rotated by the round so each workgroup alternates K (rms) and V (transposed) epilogue types
# baseline (speedup 1.0000x reference)
.LBB0_1154:
	v_readlane_b32 s2, v255, 24
	v_readlane_b32 s3, v255, 25
	s_and_b64 vcc, exec, s[2:3]
	s_cbranch_vccnz .LBB0_1209
	s_cmp_lt_u32 s92, 64
	s_cbranch_scc1 .LBB0_1209
	s_add_u32 s10, s0, 0x140e8800
	s_addc_u32 s11, s1, 0
	s_add_u32 s24, s0, 0x1b20000
	s_addc_u32 s28, s1, 0
	s_add_u32 s12, s0, 0x1aae8800
	s_addc_u32 s13, s1, 0
	s_add_u32 s0, s0, 0x17ae8800
	s_addc_u32 s1, s1, 0
	s_sub_i32 s31, s92, 0x100
	s_add_i32 s30, s92, 0xc0
	s_cmp_lt_u32 s92, 0x100
	s_cselect_b32 s31, s30, s31
	s_mov_b32 m0, s31
	s_mov_b32 s100, 0
	s_add_i32 s2, m0, s100
	s_and_b32 s2, s2, 15
	s_andn2_b32 s31, m0, 15
	s_or_b32 s31, s31, s2
	s_mov_b32 s30, s31
	s_lshl_b32 s29, s31, 3
	s_branch .LBB0_1157
.LBB0_1156:
	v_readlane_b32 s2, v254, 63
	s_add_i32 m0, m0, 0x1c0
	s_add_i32 s100, s100, 1
	s_add_i32 s2, m0, s100
	s_and_b32 s2, s2, 15
	s_andn2_b32 s31, m0, 15
	s_or_b32 s31, s31, s2
	s_mov_b32 s30, s31
	s_lshl_b32 s29, s31, 3
	s_cmp_lt_i32 m0, 0x800
	s_barrier
	s_cbranch_scc0 .LBB0_1209
